# attention units assigned statically per workgroup (no atomic grab, no LDS hand-off barrier)
# speedup vs baseline: 1.0238x; 1.0044x over previous
.LBB0_393:
	s_mov_b32 s0, 0
	v_writelane_b32 v254, s0, 20
	s_nop 0
	v_readlane_b32 s0, v254, 4
	s_add_i32 s0, s68, s0
	s_and_b32 s0, s0, 7
	s_lshl_b32 s1, s0, 8
	s_add_u32 s34, s78, s1
	s_addc_u32 s35, s79, 0
	s_lshl_b32 s69, s0, 7
	s_branch .LBB0_396

.LBB0_396:
	s_waitcnt vmcnt(0)
	s_barrier
	v_readlane_b32 s3, v254, 20
	v_readlane_b32 s2, v254, 4
	s_add_i32 s0, s3, 1
	s_lshr_b32 s2, s2, 3
	s_lshl_b32 s3, s3, 5
	v_writelane_b32 v254, s0, 20
	s_add_i32 s3, s3, s2
	v_mov_b32_e32 v0, s3
	s_movk_i32 s0, 0x7f
	s_waitcnt lgkmcnt(0)
	v_cmp_lt_i32_e32 vcc, s0, v0
	s_mov_b64 s[0:1], -1
	s_cbranch_vccnz .LBB0_395
	v_mov_b32_e32 v96, v193
	s_add_i32 s0, s3, s69
	s_bfe_u32 s2, s3, 0x10005
	v_readfirstlane_b32 s1, v96
	s_ashr_i32 s4, s0, 6
	s_and_b32 s72, s3, 31
	s_ashr_i32 s0, s1, 7
	s_lshl_b32 s3, s2, 2
	s_add_i32 s0, s0, s3
	v_bfe_u32 v97, v96, 5, 1
	s_bfe_u32 s7, s1, 0x10006
	s_lshl_b32 s36, s0, 6
	s_lshl_b32 s1, s72, 7
	s_lshl_b32 s6, s7, 6
	s_ashr_i32 s37, s36, 31
	v_lshlrev_b32_e32 v40, 3, v97
	s_or_b32 s70, s6, s1
	s_lshl_b32 s71, s4, 12
	s_lshl_b64 s[36:37], s[36:37], 1
	v_cvt_f32_ubyte0_e32 v9, v40
	v_and_b32_e32 v222, 31, v96
	s_add_u32 s52, s28, s36
	v_cmp_lt_i32_e32 vcc, v208, v209
	v_mul_f32_e32 v10, 0xbf549a78, v9
	v_or_b32_e32 v80, s70, v222
	s_addc_u32 s53, s29, s37
	v_lshlrev_b32_e32 v198, 4, v97
	v_cndmask_b32_e32 v0, v207, v208, vcc
	v_cmp_gt_f32_e32 vcc, s30, v10
	v_lshl_add_u64 v[56:57], s[52:53], 0, v[198:199]
	v_lshlrev_b32_e32 v221, 2, v0
	v_or_b32_e32 v0, s71, v80
	v_cndmask_b32_e32 v10, 0, v213, vcc
	v_mad_i64_i32 v[0:1], s[52:53], v0, s25, v[56:57]
	v_and_b32_e32 v8, 32, v96
	v_fmac_f32_e32 v10, 0xbf549a78, v9
	global_load_dwordx4 v[24:27], v[0:1], off
	global_load_dwordx4 v[28:31], v[0:1], off offset:32
	global_load_dwordx4 v[88:91], v[0:1], off offset:64
	global_load_dwordx4 v[92:95], v[0:1], off offset:96
	global_load_dwordx4 v[16:19], v8, s[14:15]
	global_load_dwordx4 v[20:23], v8, s[14:15] offset:16
	global_load_dwordx4 v[4:7], v8, s[14:15] offset:64
	s_nop 0
	global_load_dwordx4 v[0:3], v8, s[14:15] offset:80
	global_load_dwordx4 v[100:103], v8, s[14:15] offset:128
	global_load_dwordx4 v[52:55], v8, s[14:15] offset:144
	v_exp_f32_e32 v32, v10
	global_load_dwordx4 v[12:15], v8, s[14:15] offset:192
	s_nop 0
	global_load_dwordx4 v[8:11], v8, s[14:15] offset:208
	v_cndmask_b32_e32 v33, 0, v214, vcc
	s_lshr_b32 s1, s70, 6
	v_ldexp_f32 v81, v32, v33
	v_or_b32_e32 v33, 1, v40
	v_cvt_f32_ubyte0_e32 v33, v33
	v_mul_f32_e32 v34, 0xbf549a78, v33
	v_cmp_gt_f32_e32 vcc, s30, v34
	v_cvt_f32_ubyte0_e32 v41, s1
	v_mul_f32_e32 v32, v81, v41
	v_cndmask_b32_e32 v34, 0, v213, vcc
	v_fmac_f32_e32 v34, 0xbf549a78, v33
	v_cvt_f32_ubyte0_e32 v50, v222
	v_mul_f32_e32 v32, 0.15915494, v32
	v_exp_f32_e32 v33, v34
	v_sin_f32_e32 v42, v32
	v_cos_f32_e32 v43, v32
	v_mul_f32_e32 v32, v81, v50
	v_mul_f32_e32 v32, 0.15915494, v32
	v_sin_f32_e32 v62, v32
	v_cos_f32_e32 v63, v32
	v_cndmask_b32_e32 v32, 0, v214, vcc
	v_ldexp_f32 v82, v33, v32
	v_or_b32_e32 v33, 2, v40
	v_cvt_f32_ubyte0_e32 v33, v33
	v_mul_f32_e32 v34, 0xbf549a78, v33
	v_cmp_gt_f32_e32 vcc, s30, v34
	v_mul_f32_e32 v32, v82, v41
	v_mul_f32_e32 v32, 0.15915494, v32
	v_cndmask_b32_e32 v34, 0, v213, vcc
	v_fmac_f32_e32 v34, 0xbf549a78, v33
	v_exp_f32_e32 v33, v34
	v_sin_f32_e32 v45, v32
	v_cos_f32_e32 v44, v32
	v_mul_f32_e32 v32, v82, v50
	v_mul_f32_e32 v32, 0.15915494, v32
	v_sin_f32_e32 v65, v32
	v_cos_f32_e32 v64, v32
	v_cndmask_b32_e32 v32, 0, v214, vcc
	v_ldexp_f32 v83, v33, v32
	v_or_b32_e32 v33, 3, v40
	v_cvt_f32_ubyte0_e32 v33, v33
	v_mul_f32_e32 v34, 0xbf549a78, v33
	v_mul_f32_e32 v32, v83, v41
	v_cmp_gt_f32_e32 vcc, s30, v34
	v_mul_f32_e32 v32, 0.15915494, v32
	v_or_b32_e32 v35, 4, v40
	v_cndmask_b32_e32 v34, 0, v213, vcc
	v_sin_f32_e32 v46, v32
	v_cos_f32_e32 v47, v32
	v_mul_f32_e32 v32, v83, v50
	v_fmac_f32_e32 v34, 0xbf549a78, v33
	v_cvt_f32_ubyte0_e32 v35, v35
	v_mul_f32_e32 v32, 0.15915494, v32
	v_exp_f32_e32 v33, v34
	v_mul_f32_e32 v36, 0xbf549a78, v35
	v_sin_f32_e32 v70, v32
	v_cos_f32_e32 v71, v32
	v_cndmask_b32_e32 v32, 0, v214, vcc
	v_cmp_gt_f32_e32 vcc, s30, v36
	v_ldexp_f32 v84, v33, v32
	v_or_b32_e32 v37, 5, v40
	v_cndmask_b32_e32 v36, 0, v213, vcc
	v_fmac_f32_e32 v36, 0xbf549a78, v35
	v_exp_f32_e32 v35, v36
	v_mul_f32_e32 v34, v84, v50
	v_cvt_f32_ubyte0_e32 v37, v37
	v_mul_f32_e32 v34, 0.15915494, v34
	v_mul_f32_e32 v38, 0xbf549a78, v37
	v_sin_f32_e32 v73, v34
	v_cos_f32_e32 v72, v34
	v_cndmask_b32_e32 v34, 0, v214, vcc
	v_cmp_gt_f32_e32 vcc, s30, v38
	v_ldexp_f32 v85, v35, v34
	v_or_b32_e32 v39, 6, v40
	v_cndmask_b32_e32 v38, 0, v213, vcc
	v_mul_f32_e32 v36, v85, v50
	v_fmac_f32_e32 v38, 0xbf549a78, v37
	v_cvt_f32_ubyte0_e32 v39, v39
	v_mul_f32_e32 v36, 0.15915494, v36
	v_exp_f32_e32 v37, v38
	v_mul_f32_e32 v48, 0xbf549a78, v39
	v_sin_f32_e32 v74, v36
	v_cos_f32_e32 v75, v36
	v_cndmask_b32_e32 v36, 0, v214, vcc
	v_cmp_gt_f32_e32 vcc, s30, v48
	v_ldexp_f32 v86, v37, v36
	v_mul_f32_e32 v38, v86, v50
	v_cndmask_b32_e32 v48, 0, v213, vcc
	v_fmac_f32_e32 v48, 0xbf549a78, v39
	v_exp_f32_e32 v39, v48
	v_mul_f32_e32 v38, 0.15915494, v38
	v_sin_f32_e32 v77, v38
	v_cos_f32_e32 v76, v38
	v_cndmask_b32_e32 v38, 0, v214, vcc
	v_ldexp_f32 v87, v39, v38
	v_mul_f32_e32 v48, v87, v50
	v_or_b32_e32 v40, 7, v40
	v_mul_f32_e32 v48, 0.15915494, v48
	v_cvt_f32_ubyte0_e32 v40, v40
	v_sin_f32_e32 v66, v48
	v_cos_f32_e32 v67, v48
	v_mul_f32_e32 v48, 0xbf549a78, v40
	v_cmp_gt_f32_e32 vcc, s30, v48
	s_waitcnt vmcnt(0)
	v_mov_b32_e32 v49, v10
	v_lshlrev_b32_e32 v60, 16, v91
	v_cndmask_b32_e32 v48, 0, v213, vcc
	v_fmac_f32_e32 v48, 0xbf549a78, v40
	v_exp_f32_e32 v40, v48
	v_cndmask_b32_e32 v10, 0, v214, vcc
	v_and_b32_e32 v104, 0xffff0000, v91
	v_mul_f32_e32 v32, v84, v41
	v_ldexp_f32 v99, v40, v10
	v_mul_f32_e32 v10, v99, v41
	v_mul_f32_e32 v10, 0.15915494, v10
	v_mul_f32_e32 v34, v85, v41
	v_mul_f32_e32 v36, v86, v41
	v_mul_f32_e32 v38, v87, v41
	v_lshlrev_b32_e32 v61, 16, v95
	v_sin_f32_e32 v41, v10
	v_cos_f32_e32 v40, v10
	v_mul_f32_e32 v10, v99, v50
	v_and_b32_e32 v105, 0xffff0000, v95
	v_mov_b32_e32 v50, v104
	v_mov_b32_e32 v51, v60
	v_pk_mul_f32 v[106:107], v[50:51], v[50:51]
	v_mov_b32_e32 v50, v105
	v_mov_b32_e32 v51, v61
	v_pk_mul_f32 v[108:109], v[50:51], v[50:51]
	v_mov_b32_e32 v51, v8
	v_mov_b32_e32 v8, v53
	v_lshlrev_b32_e32 v112, 16, v89
	v_mov_b32_e32 v53, v14
	v_and_b32_e32 v114, 0xffff0000, v89
	v_mov_b32_e32 v14, v103
	v_lshlrev_b32_e32 v103, 16, v92
	v_and_b32_e32 v89, 0xffff0000, v92
	v_lshlrev_b32_e32 v140, 16, v25
	v_and_b32_e32 v144, 0xffff0000, v25
	v_lshlrev_b32_e32 v149, 16, v28
	v_lshlrev_b32_e32 v148, 16, v24
	v_and_b32_e32 v25, 0xffff0000, v28
	v_and_b32_e32 v24, 0xffff0000, v24
	v_mov_b32_e32 v58, v89
	v_mov_b32_e32 v59, v103
	v_lshlrev_b32_e32 v141, 16, v29
	v_and_b32_e32 v145, 0xffff0000, v29
	v_pk_mul_f32 v[150:151], v[148:149], v[148:149]
	v_pk_mul_f32 v[28:29], v[24:25], v[24:25]
	v_lshlrev_b32_e32 v113, 16, v93
	v_and_b32_e32 v115, 0xffff0000, v93
	v_pk_mul_f32 v[92:93], v[58:59], v[58:59]
	v_mov_b32_e32 v58, v22
	v_mov_b32_e32 v22, v20
	v_pk_mul_f32 v[142:143], v[140:141], v[140:141]
	v_add_f32_e32 v20, v150, v28
	v_lshlrev_b32_e32 v137, 16, v30
	v_lshlrev_b32_e32 v136, 16, v26
	v_pk_mul_f32 v[146:147], v[144:145], v[144:145]
	v_add_f32_e32 v20, v142, v20
	v_lshlrev_b32_e32 v128, 16, v27
	v_and_b32_e32 v132, 0xffff0000, v27
	v_pk_mul_f32 v[138:139], v[136:137], v[136:137]
	v_and_b32_e32 v27, 0xffff0000, v30
	v_and_b32_e32 v26, 0xffff0000, v26
	v_add_f32_e32 v20, v146, v20
	v_lshlrev_b32_e32 v129, 16, v31
	v_and_b32_e32 v133, 0xffff0000, v31
	v_pk_mul_f32 v[30:31], v[26:27], v[26:27]
	v_add_f32_e32 v20, v138, v20
	v_pk_mul_f32 v[130:131], v[128:129], v[128:129]
	v_add_f32_e32 v20, v30, v20
	v_pk_mul_f32 v[134:135], v[132:133], v[132:133]
	v_add_f32_e32 v20, v130, v20
	v_add_f32_e32 v20, v134, v20
	v_add_f32_e32 v20, v151, v20
	v_add_f32_e32 v20, v29, v20
	v_add_f32_e32 v20, v143, v20
	v_add_f32_e32 v20, v147, v20
	v_add_f32_e32 v20, v139, v20
	v_add_f32_e32 v20, v31, v20
	v_add_f32_e32 v20, v131, v20
	v_mov_b32_e32 v50, v52
	v_mov_b32_e32 v52, v102
	v_lshlrev_b32_e32 v102, 16, v88
	v_add_f32_e32 v20, v135, v20
	v_and_b32_e32 v88, 0xffff0000, v88
	v_fmac_f32_e32 v20, v102, v102
	v_fmac_f32_e32 v20, v88, v88
	v_fmac_f32_e32 v20, v112, v112
	v_lshlrev_b32_e32 v110, 16, v90
	v_fmac_f32_e32 v20, v114, v114
	v_and_b32_e32 v90, 0xffff0000, v90
	v_fmac_f32_e32 v20, v110, v110
	v_fmac_f32_e32 v20, v90, v90
	v_mul_f32_e32 v10, 0.15915494, v10
	v_lshlrev_b32_e32 v111, 16, v94
	v_and_b32_e32 v91, 0xffff0000, v94
	v_add_f32_e32 v20, v107, v20
	v_mov_b32_e32 v48, v54
	v_sin_f32_e32 v69, v10
	v_cos_f32_e32 v68, v10
	v_mov_b32_e32 v10, v55
	v_mov_b32_e32 v54, v91
	v_mov_b32_e32 v55, v111
	v_add_f32_e32 v20, v106, v20
	v_pk_mul_f32 v[94:95], v[54:55], v[54:55]
	v_mov_b32_e32 v54, v115
	v_mov_b32_e32 v55, v113
	v_add_f32_e32 v20, v93, v20
	v_pk_mul_f32 v[116:117], v[54:55], v[54:55]
	v_add_f32_e32 v20, v92, v20
	v_add_f32_e32 v20, v117, v20
	v_add_f32_e32 v20, v116, v20
	v_add_f32_e32 v20, v95, v20
	v_add_f32_e32 v20, v94, v20
	v_add_f32_e32 v20, v109, v20
	v_add_f32_e32 v20, v108, v20
	ds_bpermute_b32 v30, v221, v20
	v_mov_b32_e32 v29, v6
	v_mov_b32_e32 v28, v18
	v_mov_b32_e32 v31, v4
	v_mov_b32_e32 v54, v100
	s_waitcnt lgkmcnt(0)
	v_add_f32_e32 v6, v20, v30
	v_fmamk_f32 v6, v6, 0x3c800000, v211
	v_mul_f32_e32 v18, 0x4b800000, v6
	v_cmp_gt_f32_e32 vcc, s33, v6
	v_mov_b32_e32 v55, v12
	v_mov_b32_e32 v30, v16
	v_cndmask_b32_e32 v6, v6, v18, vcc
	v_rsq_f32_e32 v18, v6
	v_mov_b32_e32 v12, v101
	v_mov_b32_e32 v59, v2
	v_mov_b32_e32 v2, v23
	v_mul_f32_e32 v4, 0x45800000, v18
	v_cndmask_b32_e32 v16, v18, v4, vcc
	v_pk_mul_f32 v[116:117], v[54:55], v[16:17] op_sel_hi:[1,0]
	v_mov_b32_e32 v23, v0
	v_pk_mul_f32 v[102:103], v[116:117], v[102:103]
	v_pk_mul_f32 v[116:117], v[12:13], v[16:17] op_sel_hi:[1,0]
	v_mov_b32_e32 v0, v21
	v_pk_mul_f32 v[88:89], v[116:117], v[88:89]
	v_pk_mul_f32 v[116:117], v[52:53], v[16:17] op_sel_hi:[1,0]
	v_mov_b32_e32 v4, v17
	v_pk_mul_f32 v[112:113], v[116:117], v[112:113]
	v_pk_mul_f32 v[116:117], v[14:15], v[16:17] op_sel_hi:[1,0]
	v_mov_b32_e32 v6, v19
	v_pk_mul_f32 v[114:115], v[116:117], v[114:115]
	v_pk_mul_f32 v[116:117], v[50:51], v[16:17] op_sel_hi:[1,0]
	v_pk_mul_f32 v[18:19], v[30:31], v[16:17] op_sel_hi:[1,0]
	v_pk_mul_f32 v[110:111], v[116:117], v[110:111]
	v_pk_mul_f32 v[116:117], v[8:9], v[16:17] op_sel_hi:[1,0]
	v_pk_mul_f32 v[20:21], v[4:5], v[16:17] op_sel_hi:[1,0]
	v_pk_mul_f32 v[106:107], v[0:1], v[16:17] op_sel_hi:[1,0]
	v_pk_mul_f32 v[90:91], v[116:117], v[90:91]
	v_pk_mul_f32 v[116:117], v[48:49], v[16:17] op_sel_hi:[1,0]
	v_pk_mul_f32 v[18:19], v[18:19], v[148:149]
	v_pk_mul_f32 v[20:21], v[20:21], v[24:25]
	v_pk_mul_f32 v[24:25], v[28:29], v[16:17] op_sel_hi:[1,0]
	v_pk_mul_f32 v[92:93], v[6:7], v[16:17] op_sel_hi:[1,0]
	v_pk_mul_f32 v[94:95], v[22:23], v[16:17] op_sel_hi:[1,0]
	v_pk_mul_f32 v[26:27], v[106:107], v[26:27]
	v_pk_mul_f32 v[106:107], v[58:59], v[16:17] op_sel_hi:[1,0]
	v_pk_mul_f32 v[108:109], v[2:3], v[16:17] op_sel_hi:[1,0]
	v_pk_mul_f32 v[116:117], v[116:117], v[60:61]
	v_pk_mul_f32 v[16:17], v[10:11], v[16:17] op_sel_hi:[1,0]
	v_mov_b32_e32 v60, v43
	v_mov_b32_e32 v61, v42
	v_pk_mul_f32 v[104:105], v[16:17], v[104:105]
	v_pk_mul_f32 v[16:17], v[60:61], v[18:19]
	v_pk_mul_f32 v[106:107], v[106:107], v[128:129]
	v_sub_f32_e32 v16, v16, v17
	v_mul_f32_e32 v128, 0x3e38aa3b, v16
	v_pk_mul_f32 v[16:17], v[42:43], v[18:19]
	v_mov_b32_e32 v100, v63
	v_mov_b32_e32 v101, v62
	v_add_f32_e32 v16, v16, v17
	v_pk_mul_f32 v[108:109], v[108:109], v[132:133]
	v_mul_f32_e32 v132, 0x3e38aa3b, v16
	v_pk_mul_f32 v[16:17], v[100:101], v[102:103]
	v_pk_mul_f32 v[24:25], v[24:25], v[140:141]
	v_sub_f32_e32 v16, v16, v17
	v_mul_f32_e32 v100, 0x3e38aa3b, v16
	v_pk_mul_f32 v[16:17], v[62:63], v[102:103]
	v_mov_b32_e32 v62, v45
	v_add_f32_e32 v16, v16, v17
	v_mul_f32_e32 v140, 0x3e38aa3b, v16
	v_pk_mul_f32 v[16:17], v[44:45], v[20:21]
	v_mov_b32_e32 v63, v44
	v_sub_f32_e32 v16, v16, v17
	v_mul_f32_e32 v101, 0x3e38aa3b, v16
	v_pk_mul_f32 v[16:17], v[62:63], v[20:21]
	v_mov_b32_e32 v118, v65
	v_add_f32_e32 v16, v16, v17
	v_mul_f32_e32 v102, 0x3e38aa3b, v16
	v_pk_mul_f32 v[16:17], v[64:65], v[88:89]
	v_mov_b32_e32 v119, v64
	v_sub_f32_e32 v16, v16, v17
	v_mul_f32_e32 v103, 0x3e38aa3b, v16
	v_pk_mul_f32 v[16:17], v[118:119], v[88:89]
	v_mov_b32_e32 v64, v47
	v_add_f32_e32 v16, v16, v17
	v_mov_b32_e32 v65, v46
	v_mul_f32_e32 v118, 0x3e38aa3b, v16
	v_pk_mul_f32 v[16:17], v[64:65], v[24:25]
	v_mul_f32_e32 v32, 0.15915494, v32
	v_sub_f32_e32 v16, v16, v17
	v_mul_f32_e32 v119, 0x3e38aa3b, v16
	v_pk_mul_f32 v[16:17], v[46:47], v[24:25]
	v_mov_b32_e32 v120, v71
	v_mov_b32_e32 v121, v70
	v_add_f32_e32 v16, v16, v17
	v_sin_f32_e32 v33, v32
	v_cos_f32_e32 v32, v32
	v_mul_f32_e32 v133, 0x3e38aa3b, v16
	v_pk_mul_f32 v[16:17], v[120:121], v[112:113]
	v_pk_mul_f32 v[92:93], v[92:93], v[144:145]
	v_sub_f32_e32 v16, v16, v17
	v_mul_f32_e32 v120, 0x3e38aa3b, v16
	v_pk_mul_f32 v[16:17], v[70:71], v[112:113]
	v_mul_f32_e32 v35, 0.15915494, v34
	v_add_f32_e32 v16, v16, v17
	v_mul_f32_e32 v70, 0x3e38aa3b, v16
	v_pk_mul_f32 v[16:17], v[32:33], v[92:93]
	v_sin_f32_e32 v34, v35
	v_sub_f32_e32 v16, v16, v17
	v_mul_f32_e32 v71, 0x3e38aa3b, v16
	v_mov_b32_e32 v16, v33
	v_mov_b32_e32 v17, v32
	v_pk_mul_f32 v[18:19], v[16:17], v[92:93]
	v_cos_f32_e32 v35, v35
	v_add_f32_e32 v18, v18, v19
	v_mul_f32_e32 v112, 0x3e38aa3b, v18
	v_pk_mul_f32 v[18:19], v[72:73], v[114:115]
	v_mov_b32_e32 v122, v73
	v_mov_b32_e32 v123, v72
	v_sub_f32_e32 v18, v18, v19
	v_mul_f32_e32 v72, 0x3e38aa3b, v18
	v_pk_mul_f32 v[18:19], v[122:123], v[114:115]
	v_pk_mul_f32 v[94:95], v[94:95], v[136:137]
	v_add_f32_e32 v18, v18, v19
	v_mul_f32_e32 v73, 0x3e38aa3b, v18
	v_mov_b32_e32 v18, v35
	v_mov_b32_e32 v19, v34
	v_pk_mul_f32 v[20:21], v[18:19], v[94:95]
	v_mul_f32_e32 v36, 0.15915494, v36
	v_sub_f32_e32 v20, v20, v21
	v_mul_f32_e32 v113, 0x3e38aa3b, v20
	v_pk_mul_f32 v[20:21], v[34:35], v[94:95]
	v_mov_b32_e32 v124, v75
	v_mov_b32_e32 v125, v74
	v_add_f32_e32 v20, v20, v21
	v_sin_f32_e32 v37, v36
	v_cos_f32_e32 v36, v36
	v_mul_f32_e32 v114, 0x3e38aa3b, v20
	v_pk_mul_f32 v[20:21], v[124:125], v[110:111]
	v_mul_f32_e32 v39, 0.15915494, v38
	v_sub_f32_e32 v20, v20, v21
	v_mul_f32_e32 v115, 0x3e38aa3b, v20
	v_pk_mul_f32 v[20:21], v[74:75], v[110:111]
	v_sin_f32_e32 v38, v39
	v_add_f32_e32 v20, v20, v21
	v_mul_f32_e32 v74, 0x3e38aa3b, v20
	v_pk_mul_f32 v[20:21], v[36:37], v[26:27]
	v_cos_f32_e32 v39, v39
	v_sub_f32_e32 v20, v20, v21
	v_mul_f32_e32 v75, 0x3e38aa3b, v20
	v_mov_b32_e32 v20, v37
	v_mov_b32_e32 v21, v36
	v_pk_mul_f32 v[24:25], v[20:21], v[26:27]
	v_mov_b32_e32 v126, v77
	v_add_f32_e32 v24, v24, v25
	v_mul_f32_e32 v110, 0x3e38aa3b, v24
	v_pk_mul_f32 v[24:25], v[76:77], v[90:91]
	v_mov_b32_e32 v127, v76
	v_sub_f32_e32 v24, v24, v25
	v_mul_f32_e32 v76, 0x3e38aa3b, v24
	v_pk_mul_f32 v[24:25], v[126:127], v[90:91]
	v_mov_b32_e32 v78, v67
	v_add_f32_e32 v24, v24, v25
	v_or_b32_e32 v25, 32, v80
	v_or_b32_e32 v25, s71, v25
	v_mad_i64_i32 v[56:57], s[52:53], v25, s25, v[56:57]
	v_mul_f32_e32 v77, 0x3e38aa3b, v24
	v_mov_b32_e32 v24, v39
	v_mov_b32_e32 v25, v38
	v_pk_mul_f32 v[26:27], v[24:25], v[106:107]
	v_mov_b32_e32 v79, v66
	v_sub_f32_e32 v26, v26, v27
	v_mul_f32_e32 v111, 0x3e38aa3b, v26
	v_pk_mul_f32 v[26:27], v[38:39], v[106:107]
	global_load_dwordx4 v[88:91], v[56:57], off offset:64
	global_load_dwordx4 v[92:95], v[56:57], off offset:96
	v_add_f32_e32 v26, v26, v27
	v_mul_f32_e32 v106, 0x3e38aa3b, v26
	v_pk_mul_f32 v[26:27], v[78:79], v[116:117]
	v_cvt_pk_bf16_f32 v128, v128, v101
	v_cvt_pk_bf16_f32 v132, v132, v102
	v_cvt_pk_bf16_f32 v136, v100, v103
	v_cvt_pk_bf16_f32 v130, v113, v75
	v_cvt_pk_bf16_f32 v142, v74, v77
	s_nop 0
	v_sub_f32_e32 v26, v26, v27
	v_mul_f32_e32 v78, 0x3e38aa3b, v26
	v_pk_mul_f32 v[26:27], v[66:67], v[116:117]
	v_cvt_pk_bf16_f32 v137, v120, v72
	v_cvt_pk_bf16_f32 v141, v70, v73
	v_cvt_pk_bf16_f32 v129, v119, v71
	v_cvt_pk_bf16_f32 v138, v115, v76
	v_cvt_pk_bf16_f32 v134, v114, v110
	s_nop 0
	v_add_f32_e32 v26, v26, v27
	v_mul_f32_e32 v79, 0x3e38aa3b, v26
	v_pk_mul_f32 v[26:27], v[40:41], v[108:109]
	v_cvt_pk_bf16_f32 v140, v140, v118
	v_cvt_pk_bf16_f32 v133, v133, v112
	v_and_b32_e32 v98, 63, v96
	v_sub_f32_e32 v26, v26, v27
	v_mul_f32_e32 v107, 0x3e38aa3b, v26
	v_mov_b32_e32 v26, v41
	v_mov_b32_e32 v27, v40
	v_pk_mul_f32 v[66:67], v[26:27], v[108:109]
	v_cvt_pk_bf16_f32 v131, v111, v107
	s_ashr_i32 s1, s0, 31
	v_add_f32_e32 v66, v66, v67
	v_mul_f32_e32 v108, 0x3e38aa3b, v66
	v_pk_mul_f32 v[66:67], v[68:69], v[104:105]
	v_cvt_pk_bf16_f32 v135, v106, v108
	s_lshl_b64 s[0:1], s[0:1], 2
	v_sub_f32_e32 v66, v66, v67
	v_mul_f32_e32 v109, 0x3e38aa3b, v66
	v_mov_b32_e32 v66, v69
	v_mov_b32_e32 v67, v68
	v_pk_mul_f32 v[66:67], v[66:67], v[104:105]
	global_load_dwordx4 v[100:103], v[56:57], off
	global_load_dwordx4 v[104:107], v[56:57], off offset:32
	v_bitop3_b32 v56, v80, 63, 32 bitop3:0xc8
	v_cvt_f32_ubyte0_e32 v56, v56
	v_mul_f32_e32 v57, v81, v56
	v_mul_f32_e32 v57, 0.15915494, v57
	v_sin_f32_e32 v80, v57
	v_cos_f32_e32 v81, v57
	v_mul_f32_e32 v57, v82, v56
	v_mul_f32_e32 v57, 0.15915494, v57
	v_cvt_pk_bf16_f32 v139, v78, v109
	v_sin_f32_e32 v109, v57
	v_cos_f32_e32 v108, v57
	v_mul_f32_e32 v57, v83, v56
	v_mul_f32_e32 v57, 0.15915494, v57
	v_sin_f32_e32 v74, v57
	v_cos_f32_e32 v75, v57
	v_mul_f32_e32 v57, v84, v56
	v_mul_f32_e32 v57, 0.15915494, v57
	v_sin_f32_e32 v73, v57
	v_cos_f32_e32 v72, v57
	v_mul_f32_e32 v57, v85, v56
	v_mul_f32_e32 v57, 0.15915494, v57
	v_sin_f32_e32 v70, v57
	v_cos_f32_e32 v71, v57
	v_mul_f32_e32 v57, v86, v56
	v_mul_f32_e32 v57, 0.15915494, v57
	v_sin_f32_e32 v69, v57
	v_cos_f32_e32 v68, v57
	v_mul_f32_e32 v57, v87, v56
	v_mul_f32_e32 v56, v99, v56
	v_mov_b32_e32 v122, v81
	v_mov_b32_e32 v123, v80
	v_mov_b32_e32 v124, v109
	v_mov_b32_e32 v125, v108
	v_add_f32_e32 v66, v66, v67
	v_mul_f32_e32 v66, 0x3e38aa3b, v66
	v_cvt_pk_bf16_f32 v143, v79, v66
	v_mov_b32_e32 v78, v75
	v_mov_b32_e32 v79, v74
	s_waitcnt vmcnt(3)
	v_lshlrev_b32_e32 v82, 16, v91
	v_and_b32_e32 v84, 0xffff0000, v91
	s_waitcnt vmcnt(2)
	v_lshlrev_b32_e32 v83, 16, v95
	v_and_b32_e32 v85, 0xffff0000, v95
	v_mov_b32_e32 v76, v84
	v_mov_b32_e32 v77, v82
	v_pk_mul_f32 v[86:87], v[76:77], v[76:77]
	v_mov_b32_e32 v76, v85
	v_mov_b32_e32 v77, v83
	v_lshlrev_b32_e32 v113, 16, v94
	v_and_b32_e32 v91, 0xffff0000, v94
	v_pk_mul_f32 v[110:111], v[76:77], v[76:77]
	v_mov_b32_e32 v76, v91
	v_mov_b32_e32 v77, v113
	v_lshlrev_b32_e32 v115, 16, v93
	v_and_b32_e32 v117, 0xffff0000, v93
	v_pk_mul_f32 v[94:95], v[76:77], v[76:77]
	v_lshlrev_b32_e32 v114, 16, v89
	v_and_b32_e32 v116, 0xffff0000, v89
	v_mov_b32_e32 v76, v117
	v_mov_b32_e32 v77, v115
	v_lshlrev_b32_e32 v121, 16, v92
	v_and_b32_e32 v89, 0xffff0000, v92
	v_pk_mul_f32 v[118:119], v[76:77], v[76:77]
	v_mov_b32_e32 v76, v89
	v_mov_b32_e32 v77, v121
	v_pk_mul_f32 v[92:93], v[76:77], v[76:77]
	v_lshlrev_b32_e32 v120, 16, v88
	v_and_b32_e32 v88, 0xffff0000, v88
	v_lshlrev_b32_e32 v112, 16, v90
	v_and_b32_e32 v90, 0xffff0000, v90
	v_mov_b32_e32 v76, v73
	v_mul_f32_e32 v57, 0.15915494, v57
	v_sin_f32_e32 v66, v57
	v_cos_f32_e32 v67, v57
	s_add_u32 s0, s18, s0
	s_addc_u32 s1, s19, s1
	v_mul_f32_e32 v56, 0.15915494, v56
	v_sin_f32_e32 v57, v56
	v_cos_f32_e32 v56, v56
	s_waitcnt vmcnt(1)
	v_lshlrev_b32_e32 v154, 16, v101
	v_and_b32_e32 v158, 0xffff0000, v101
	s_waitcnt vmcnt(0)
	v_lshlrev_b32_e32 v163, 16, v104
	v_lshlrev_b32_e32 v162, 16, v100
	v_and_b32_e32 v101, 0xffff0000, v104
	v_and_b32_e32 v100, 0xffff0000, v100
	v_lshlrev_b32_e32 v155, 16, v105
	v_and_b32_e32 v159, 0xffff0000, v105
	v_pk_mul_f32 v[164:165], v[162:163], v[162:163]
	v_pk_mul_f32 v[104:105], v[100:101], v[100:101]
	v_pk_mul_f32 v[156:157], v[154:155], v[154:155]
	v_add_f32_e32 v77, v164, v104
	v_lshlrev_b32_e32 v151, 16, v106
	v_lshlrev_b32_e32 v150, 16, v102
	v_pk_mul_f32 v[160:161], v[158:159], v[158:159]
	v_add_f32_e32 v77, v156, v77
	v_lshlrev_b32_e32 v126, 16, v103
	v_and_b32_e32 v146, 0xffff0000, v103
	v_pk_mul_f32 v[152:153], v[150:151], v[150:151]
	v_and_b32_e32 v103, 0xffff0000, v106
	v_and_b32_e32 v102, 0xffff0000, v102
	v_add_f32_e32 v77, v160, v77
	v_lshlrev_b32_e32 v127, 16, v107
	v_and_b32_e32 v147, 0xffff0000, v107
	v_pk_mul_f32 v[106:107], v[102:103], v[102:103]
	v_add_f32_e32 v77, v152, v77
	v_pk_mul_f32 v[144:145], v[126:127], v[126:127]
	v_add_f32_e32 v77, v106, v77
	v_pk_mul_f32 v[148:149], v[146:147], v[146:147]
	v_add_f32_e32 v77, v144, v77
	v_add_f32_e32 v77, v148, v77
	v_add_f32_e32 v77, v165, v77
	v_add_f32_e32 v77, v105, v77
	v_add_f32_e32 v77, v157, v77
	v_add_f32_e32 v77, v161, v77
	v_add_f32_e32 v77, v153, v77
	v_add_f32_e32 v77, v107, v77
	v_add_f32_e32 v77, v145, v77
	v_add_f32_e32 v77, v149, v77
	v_fmac_f32_e32 v77, v120, v120
	v_fmac_f32_e32 v77, v88, v88
	v_fmac_f32_e32 v77, v114, v114
	v_fmac_f32_e32 v77, v116, v116
	v_fmac_f32_e32 v77, v112, v112
	v_fmac_f32_e32 v77, v90, v90
	v_add_f32_e32 v77, v87, v77
	v_add_f32_e32 v77, v86, v77
	v_add_f32_e32 v77, v93, v77
	v_add_f32_e32 v77, v92, v77
	v_add_f32_e32 v77, v119, v77
	v_add_f32_e32 v77, v118, v77
	v_add_f32_e32 v77, v95, v77
	v_add_f32_e32 v77, v94, v77
	v_add_f32_e32 v77, v111, v77
	v_add_f32_e32 v93, v110, v77
	ds_bpermute_b32 v94, v221, v93
	v_mov_b32_e32 v77, v72
	v_mov_b32_e32 v86, v71
	v_mov_b32_e32 v87, v70
	v_mov_b32_e32 v92, v69
	s_waitcnt lgkmcnt(0)
	v_add_f32_e32 v93, v93, v94
	v_fmamk_f32 v93, v93, 0x3c800000, v211
	v_mul_f32_e32 v94, 0x4b800000, v93
	v_cmp_gt_f32_e32 vcc, s33, v93
	v_mov_b32_e32 v95, v66
	s_lshl_b32 s52, s4, 8
	v_cndmask_b32_e32 v93, v93, v94, vcc
	v_rsq_f32_e32 v99, v93
	v_mov_b32_e32 v93, v68
	v_mov_b32_e32 v94, v67
	s_ashr_i32 s53, s52, 31
	v_mul_f32_e32 v104, 0x45800000, v99
	v_cndmask_b32_e32 v104, v99, v104, vcc
	v_pk_mul_f32 v[30:31], v[30:31], v[104:105] op_sel_hi:[1,0]
	v_pk_mul_f32 v[54:55], v[54:55], v[104:105] op_sel_hi:[1,0]
	v_pk_mul_f32 v[30:31], v[30:31], v[162:163]
	v_pk_mul_f32 v[54:55], v[54:55], v[120:121]
	v_pk_mul_f32 v[60:61], v[60:61], v[30:31]
	v_pk_mul_f32 v[30:31], v[42:43], v[30:31]
	v_pk_mul_f32 v[4:5], v[4:5], v[104:105] op_sel_hi:[1,0]
	v_add_f32_e32 v30, v30, v31
	v_mul_f32_e32 v42, 0x3e38aa3b, v30
	v_pk_mul_f32 v[30:31], v[122:123], v[54:55]
	v_pk_mul_f32 v[4:5], v[4:5], v[100:101]
	v_sub_f32_e32 v30, v30, v31
	v_mul_f32_e32 v43, 0x3e38aa3b, v30
	v_pk_mul_f32 v[30:31], v[80:81], v[54:55]
	v_pk_mul_f32 v[12:13], v[12:13], v[104:105] op_sel_hi:[1,0]
	v_add_f32_e32 v30, v30, v31
	v_mul_f32_e32 v54, 0x3e38aa3b, v30
	v_pk_mul_f32 v[30:31], v[44:45], v[4:5]
	v_pk_mul_f32 v[4:5], v[62:63], v[4:5]
	v_pk_mul_f32 v[12:13], v[12:13], v[88:89]
	v_add_f32_e32 v4, v4, v5
	v_sub_f32_e32 v30, v30, v31
	v_mul_f32_e32 v31, 0x3e38aa3b, v4
	v_pk_mul_f32 v[4:5], v[108:109], v[12:13]
	v_pk_mul_f32 v[28:29], v[28:29], v[104:105] op_sel_hi:[1,0]
	v_sub_f32_e32 v4, v4, v5
	v_mul_f32_e32 v44, 0x3e38aa3b, v4
	v_pk_mul_f32 v[4:5], v[124:125], v[12:13]
	v_pk_mul_f32 v[28:29], v[28:29], v[154:155]
	v_add_f32_e32 v4, v4, v5
	v_mul_f32_e32 v12, 0x3e38aa3b, v4
	v_pk_mul_f32 v[4:5], v[64:65], v[28:29]
	v_pk_mul_f32 v[52:53], v[52:53], v[104:105] op_sel_hi:[1,0]
	v_sub_f32_e32 v4, v4, v5
	v_mul_f32_e32 v13, 0x3e38aa3b, v4
	v_pk_mul_f32 v[4:5], v[46:47], v[28:29]
	v_lshlrev_b32_e32 v28, 2, v98
	global_load_dword v29, v28, s[14:15]
	v_pk_mul_f32 v[52:53], v[52:53], v[114:115]
	global_load_dword v28, v28, s[16:17]
	v_add_f32_e32 v4, v4, v5
	v_mul_f32_e32 v45, 0x3e38aa3b, v4
	v_pk_mul_f32 v[4:5], v[78:79], v[52:53]
	v_pk_mul_f32 v[6:7], v[6:7], v[104:105] op_sel_hi:[1,0]
	v_sub_f32_e32 v4, v4, v5
	v_mul_f32_e32 v46, 0x3e38aa3b, v4
	v_pk_mul_f32 v[4:5], v[74:75], v[52:53]
	v_pk_mul_f32 v[6:7], v[6:7], v[158:159]
	v_add_f32_e32 v4, v4, v5
	v_mul_f32_e32 v47, 0x3e38aa3b, v4
	v_pk_mul_f32 v[4:5], v[32:33], v[6:7]
	v_pk_mul_f32 v[14:15], v[14:15], v[104:105] op_sel_hi:[1,0]
	v_sub_f32_e32 v4, v4, v5
	v_mul_f32_e32 v32, 0x3e38aa3b, v4
	v_pk_mul_f32 v[4:5], v[16:17], v[6:7]
	v_pk_mul_f32 v[14:15], v[14:15], v[116:117]
	v_add_f32_e32 v4, v4, v5
	v_mul_f32_e32 v6, 0x3e38aa3b, v4
	v_pk_mul_f32 v[4:5], v[72:73], v[14:15]
	v_pk_mul_f32 v[22:23], v[22:23], v[104:105] op_sel_hi:[1,0]
	v_sub_f32_e32 v4, v4, v5
	v_mul_f32_e32 v7, 0x3e38aa3b, v4
	v_pk_mul_f32 v[4:5], v[76:77], v[14:15]
	v_pk_mul_f32 v[22:23], v[22:23], v[150:151]
	v_add_f32_e32 v4, v4, v5
	v_mul_f32_e32 v14, 0x3e38aa3b, v4
	v_pk_mul_f32 v[4:5], v[18:19], v[22:23]
	v_pk_mul_f32 v[50:51], v[50:51], v[104:105] op_sel_hi:[1,0]
	v_sub_f32_e32 v4, v4, v5
	v_mul_f32_e32 v15, 0x3e38aa3b, v4
	v_pk_mul_f32 v[4:5], v[34:35], v[22:23]
	v_pk_mul_f32 v[50:51], v[50:51], v[112:113]
	v_add_f32_e32 v4, v4, v5
	v_mul_f32_e32 v16, 0x3e38aa3b, v4
	v_pk_mul_f32 v[4:5], v[86:87], v[50:51]
	v_pk_mul_f32 v[0:1], v[0:1], v[104:105] op_sel_hi:[1,0]
	v_sub_f32_e32 v4, v4, v5
	v_mul_f32_e32 v17, 0x3e38aa3b, v4
	v_pk_mul_f32 v[4:5], v[70:71], v[50:51]
	v_pk_mul_f32 v[0:1], v[0:1], v[102:103]
	v_add_f32_e32 v4, v4, v5
	v_pk_mul_f32 v[8:9], v[8:9], v[104:105] op_sel_hi:[1,0]
	v_mul_f32_e32 v18, 0x3e38aa3b, v4
	v_pk_mul_f32 v[4:5], v[36:37], v[0:1]
	v_pk_mul_f32 v[0:1], v[20:21], v[0:1]
	v_pk_mul_f32 v[8:9], v[8:9], v[90:91]
	v_add_f32_e32 v0, v0, v1
	v_sub_f32_e32 v4, v4, v5
	v_mul_f32_e32 v5, 0x3e38aa3b, v0
	v_pk_mul_f32 v[0:1], v[68:69], v[8:9]
	v_pk_mul_f32 v[58:59], v[58:59], v[104:105] op_sel_hi:[1,0]
	v_sub_f32_e32 v0, v0, v1
	v_mul_f32_e32 v19, 0x3e38aa3b, v0
	v_pk_mul_f32 v[0:1], v[92:93], v[8:9]
	v_pk_mul_f32 v[58:59], v[58:59], v[126:127]
	v_add_f32_e32 v0, v0, v1
	v_mul_f32_e32 v8, 0x3e38aa3b, v0
	v_pk_mul_f32 v[0:1], v[24:25], v[58:59]
	v_pk_mul_f32 v[48:49], v[48:49], v[104:105] op_sel_hi:[1,0]
	v_sub_f32_e32 v0, v0, v1
	v_mul_f32_e32 v9, 0x3e38aa3b, v0
	v_pk_mul_f32 v[0:1], v[38:39], v[58:59]
	v_pk_mul_f32 v[48:49], v[48:49], v[82:83]
	v_add_f32_e32 v0, v0, v1
	v_mul_f32_e32 v20, 0x3e38aa3b, v0
	v_pk_mul_f32 v[0:1], v[94:95], v[48:49]
	v_pk_mul_f32 v[2:3], v[2:3], v[104:105] op_sel_hi:[1,0]
	v_sub_f32_e32 v0, v0, v1
	v_mul_f32_e32 v21, 0x3e38aa3b, v0
	v_pk_mul_f32 v[0:1], v[66:67], v[48:49]
	v_pk_mul_f32 v[2:3], v[2:3], v[146:147]
	v_add_f32_e32 v0, v0, v1
	v_mul_f32_e32 v22, 0x3e38aa3b, v0
	v_pk_mul_f32 v[0:1], v[40:41], v[2:3]
	v_pk_mul_f32 v[10:11], v[10:11], v[104:105] op_sel_hi:[1,0]
	v_sub_f32_e32 v0, v0, v1
	v_mul_f32_e32 v23, 0x3e38aa3b, v0
	v_pk_mul_f32 v[0:1], v[26:27], v[2:3]
	global_load_dword v2, v199, s[0:1]
	v_pk_mul_f32 v[10:11], v[10:11], v[84:85]
	v_add_f32_e32 v0, v0, v1
	v_mul_f32_e32 v3, 0x3e38aa3b, v0
	v_pk_mul_f32 v[0:1], v[56:57], v[10:11]
	v_cmp_lt_i32_e32 vcc, v215, v209
	v_sub_f32_e32 v0, v0, v1
	v_mul_f32_e32 v24, 0x3e38aa3b, v0
	v_mov_b32_e32 v0, v57
	v_mov_b32_e32 v1, v56
	v_pk_mul_f32 v[0:1], v[0:1], v[10:11]
	v_mul_f32_e32 v4, 0x3e38aa3b, v4
	v_add_f32_e32 v0, v0, v1
	v_cndmask_b32_e32 v1, v207, v215, vcc
	v_mul_f32_e32 v10, 0x3e38aa3b, v0
	s_waitcnt vmcnt(2)
	v_and_b32_e32 v0, 0x7fffffff, v29
	v_lshlrev_b32_e32 v223, 2, v1
	ds_bpermute_b32 v0, v223, v0
	s_waitcnt vmcnt(1)
	v_and_b32_e32 v1, 0x7fffffff, v28
	ds_bpermute_b32 v1, v223, v1
	v_cmp_lt_i32_e32 vcc, v216, v209
	v_cvt_pk_bf16_f32 v146, v15, v4
	v_cvt_pk_bf16_f32 v147, v9, v23
	s_waitcnt lgkmcnt(1)
	v_max_f32_e32 v0, v0, v0
	v_max_f32_e64 v4, |v29|, |v29|
	v_cndmask_b32_e32 v9, v207, v216, vcc
	v_max_f32_e32 v0, v4, v0
	v_lshlrev_b32_e32 v224, 2, v9
	s_waitcnt lgkmcnt(0)
	v_max_f32_e32 v1, v1, v1
	v_max_f32_e64 v4, |v28|, |v28|
	ds_bpermute_b32 v9, v224, v0
	v_max_f32_e32 v1, v4, v1
	ds_bpermute_b32 v4, v224, v1
	v_cvt_pk_bf16_f32 v150, v16, v5
	v_cmp_lt_i32_e32 vcc, v217, v209
	s_waitcnt lgkmcnt(1)
	v_max_f32_e32 v5, v9, v9
	v_max_f32_e32 v0, v0, v5
	v_cndmask_b32_e32 v5, v207, v217, vcc
	s_waitcnt lgkmcnt(0)
	v_max_f32_e32 v4, v4, v4
	v_lshlrev_b32_e32 v5, 2, v5
	v_cvt_pk_bf16_f32 v149, v45, v6
	ds_bpermute_b32 v6, v5, v0
	v_max_f32_e32 v1, v1, v4
	ds_bpermute_b32 v4, v5, v1
	v_cvt_pk_bf16_f32 v151, v20, v3
	v_cmp_lt_i32_e32 vcc, v218, v209
	s_waitcnt lgkmcnt(1)
	v_max_f32_e32 v3, v6, v6
	v_max_f32_e32 v0, v0, v3
	s_waitcnt lgkmcnt(0)
	v_max_f32_e32 v3, v4, v4
	v_cndmask_b32_e32 v4, v207, v218, vcc
	v_lshlrev_b32_e32 v4, 2, v4
	ds_bpermute_b32 v5, v4, v0
	v_max_f32_e32 v1, v1, v3
	ds_bpermute_b32 v3, v4, v1
	v_cmp_lt_i32_e32 vcc, v219, v209
	s_mov_b32 s0, 0x3fb8aa3b
	s_waitcnt lgkmcnt(1)
	v_max_f32_e32 v4, v5, v5
	v_max_f32_e32 v0, v0, v4
	v_cndmask_b32_e32 v4, v207, v219, vcc
	s_waitcnt lgkmcnt(0)
	v_max_f32_e32 v3, v3, v3
	v_lshlrev_b32_e32 v4, 2, v4
	ds_bpermute_b32 v5, v4, v0
	v_max_f32_e32 v1, v1, v3
	ds_bpermute_b32 v3, v4, v1
	v_ashrrev_i32_e32 v200, 2, v96
	v_ashrrev_i32_e32 v201, 31, v200
	s_waitcnt lgkmcnt(1)
	v_max_f32_e32 v4, v5, v5
	v_max_f32_e32 v0, v0, v4
	s_waitcnt lgkmcnt(0)
	v_max_f32_e32 v3, v3, v3
	ds_bpermute_b32 v4, v221, v0
	v_max_f32_e32 v1, v1, v3
	ds_bpermute_b32 v3, v221, v1
	v_bfe_u32 v225, v96, 1, 1
	v_and_b32_e32 v226, 1, v96
	s_waitcnt lgkmcnt(1)
	v_max_f32_e32 v4, v4, v4
	v_max_f32_e32 v0, v0, v4
	s_waitcnt lgkmcnt(0)
	v_max_f32_e32 v3, v3, v3
	v_max_f32_e32 v1, v1, v3
	v_mul_f32_e32 v0, 0x41000000, v0
	v_mul_f32_e32 v0, v1, v0
	v_mul_f32_e32 v0, 0x3fb8aa3b, v0
	s_waitcnt vmcnt(0)
	v_mul_f32_e32 v235, 0x3fb8aa3b, v2
	v_fmamk_f32 v0, v0, 0x3f828f5c, v212
	v_max_f32_e32 v4, v0, v235
	v_fma_f32 v5, v2, s0, -v4
	s_add_u32 s0, s52, 0x10000
	s_addc_u32 s1, s53, 0
	v_lshl_add_u64 v[0:1], s[0:1], 0, v[200:201]
	v_mov_b64_e32 v[2:3], s[28:29]
	v_mad_u64_u32 v[2:3], s[0:1], v0, s25, v[2:3]
	v_mad_i32_i24 v3, v1, s25, v3
	s_lshl_b32 s8, s2, 7
	v_lshl_add_u64 v[0:1], v[2:3], 0, s[8:9]
	v_lshlrev_b32_e32 v198, 6, v225
	v_and_b32_e32 v6, 3, v96
	v_lshl_add_u64 v[2:3], v[0:1], 0, v[198:199]
	v_lshlrev_b32_e32 v198, 4, v226
	v_lshl_add_u64 v[2:3], v[2:3], 0, v[198:199]
	v_lshlrev_b32_e32 v198, 5, v6
	v_lshl_add_u64 v[0:1], v[0:1], 0, v[198:199]
	global_load_dwordx4 v[88:91], v[2:3], off offset:1024
	global_load_dwordx4 v[92:95], v[2:3], off offset:1056
	global_load_dwordx4 v[80:83], v[0:1], off offset:1296
	global_load_dwordx4 v[84:87], v[0:1], off offset:1280
	v_exp_f32_e32 v0, v5
	v_cmp_gt_f32_e32 vcc, s31, v4
	v_cmp_gt_u32_e64 s[0:1], 32, v98
	s_ashr_i32 s5, s4, 31
	v_cndmask_b32_e32 v0, 1.0, v0, vcc
	s_lshl_b32 s85, s7, 1
	v_cndmask_b32_e64 v227, 0, v0, s[0:1]
	s_add_i32 s84, s72, -2
	s_lshl_b64 s[0:1], s[4:5], 12
	s_or_b32 s86, s85, 1
	v_lshlrev_b32_e32 v1, 4, v96
	v_lshl_add_u32 v0, v225, 13, 0
	s_add_u32 s52, s52, 0x10080
	v_and_b32_e32 v1, 0xc0, v1
	v_lshlrev_b32_e32 v2, 1, v96
	v_sub_f32_e32 v60, v60, v61
	v_mul_f32_e32 v30, 0x3e38aa3b, v30
	v_cvt_pk_bf16_f32 v154, v17, v19
	v_cvt_pk_bf16_f32 v155, v21, v24
	v_cvt_pk_bf16_f32 v157, v47, v14
	v_cvt_pk_bf16_f32 v158, v18, v8
	v_cvt_pk_bf16_f32 v159, v22, v10
	v_lshlrev_b32_e32 v16, 5, v225
	v_lshlrev_b32_e32 v18, 3, v226
	v_lshlrev_b32_e32 v20, 4, v6
	v_lshl_add_u32 v17, v226, 11, v0
	v_lshlrev_b32_e32 v19, 4, v200
	v_lshl_add_u32 v21, v200, 6, v0
	v_lshlrev_b32_e32 v22, 5, v226
	v_lshlrev_b32_e32 v0, 4, v222
	s_addc_u32 s53, s53, 0
	v_lshl_or_b32 v1, v97, 8, v1
	v_and_b32_e32 v2, 32, v2
	v_lshlrev_b32_e32 v3, 3, v6
	v_mov_b32_e32 v14, v199
	v_mov_b32_e32 v15, v199
	v_mul_f32_e32 v60, 0x3e38aa3b, v60
	v_cvt_pk_bf16_f32 v144, v60, v30
	v_cvt_pk_bf16_f32 v145, v13, v32
	v_cvt_pk_bf16_f32 v148, v42, v31
	v_cvt_pk_bf16_f32 v152, v43, v44
	v_cvt_pk_bf16_f32 v153, v46, v7
	v_cvt_pk_bf16_f32 v156, v54, v12
	v_cmp_ngt_f32_e64 s[2:3], s31, v4
	v_cndmask_b32_e64 v48, 0, -v4, vcc
	v_cmp_gt_u32_e64 s[4:5], 2, v6
	v_or_b32_e32 v229, s6, v222
	s_add_u32 s54, s28, s8
	v_or3_b32 v231, v1, v2, v3
	v_lshl_or_b32 v232, v97, 11, v0
	v_mov_b32_e32 v0, v199
	v_mov_b32_e32 v1, v199
	v_mov_b32_e32 v2, v199
	v_mov_b32_e32 v3, v199
	v_mov_b32_e32 v4, v199
	v_mov_b32_e32 v5, v199
	v_mov_b32_e32 v6, v199
	v_mov_b32_e32 v7, v199
	v_mov_b32_e32 v8, v199
	v_mov_b32_e32 v9, v199
	v_mov_b32_e32 v10, v199
	v_mov_b32_e32 v11, v199
	v_mov_b32_e32 v12, v199
	v_mov_b32_e32 v13, v199
	v_lshlrev_b32_e32 v198, 1, v16
	v_lshlrev_b32_e32 v202, 1, v18
	v_lshlrev_b32_e32 v204, 1, v20
	v_add_u32_e32 v233, v17, v19
	v_add_u32_e32 v234, v21, v22
	v_mov_b64_e32 v[30:31], v[14:15]
	v_mov_b64_e32 v[46:47], v[14:15]
	v_mov_b64_e32 v[78:79], v[14:15]
	s_mov_b32 s73, 0
	v_lshlrev_b32_e32 v228, 2, v97
	v_mov_b32_e32 v49, v48
	v_mov_b32_e32 v50, v48
	v_mov_b32_e32 v51, v48
	v_mov_b32_e32 v52, v48
	v_mov_b32_e32 v53, v48
	v_mov_b32_e32 v54, v48
	v_mov_b32_e32 v55, v48
	v_mov_b32_e32 v56, v48
	v_mov_b32_e32 v57, v48
	v_mov_b32_e32 v58, v48
	v_mov_b32_e32 v59, v48
	v_mov_b32_e32 v60, v48
	v_mov_b32_e32 v61, v48
	v_mov_b32_e32 v62, v48
	v_mov_b32_e32 v63, v48
	v_or_b32_e32 v230, 32, v229
	s_addc_u32 s55, s29, 0
	v_mov_b32_e32 v113, v235
	v_mov_b32_e32 v112, v227
	v_mov_b64_e32 v[28:29], v[12:13]
	v_mov_b64_e32 v[26:27], v[10:11]
	v_mov_b64_e32 v[24:25], v[8:9]
	v_mov_b64_e32 v[22:23], v[6:7]
	v_mov_b64_e32 v[20:21], v[4:5]
	v_mov_b64_e32 v[18:19], v[2:3]
	v_mov_b64_e32 v[16:17], v[0:1]
	v_mov_b64_e32 v[44:45], v[12:13]
	v_mov_b64_e32 v[42:43], v[10:11]
	v_mov_b64_e32 v[40:41], v[8:9]
	v_mov_b64_e32 v[38:39], v[6:7]
	v_mov_b64_e32 v[36:37], v[4:5]
	v_mov_b64_e32 v[34:35], v[2:3]
	v_mov_b64_e32 v[32:33], v[0:1]
	v_mov_b64_e32 v[76:77], v[12:13]
	v_mov_b64_e32 v[74:75], v[10:11]
	v_mov_b64_e32 v[72:73], v[8:9]
	v_mov_b64_e32 v[70:71], v[6:7]
	v_mov_b64_e32 v[68:69], v[4:5]
	v_mov_b64_e32 v[66:67], v[2:3]
	v_mov_b64_e32 v[64:65], v[0:1]
	s_mov_b64 s[6:7], -1
	s_cmp_lt_u32 s73, 2
	s_mov_b32 s8, 0
	s_cbranch_scc1 .LBB0_408
